# code placement: peeled first-iteration entry of each GEMM loop aligned to 64 bytes like the loop head
# speedup vs baseline: 1.0046x; 1.0039x over previous
.Lpr_446:
	s_branch .Lmid1_446
	.p2alignl 6, 3212836864
